# P3 queue in two passes: all NSA items (decreasing cost) then all MLA items (decreasing cost), cheapest items at the tail
# baseline (speedup 1.0000x reference)
; #define SCHED_BARRIER() __builtin_amdgcn_sched_barrier(0)
; __global__ void __launch_bounds__(512) mega(Params p) {
;     ...
; #pragma unroll 1
;       for (int grp = 0; grp < 8; ++grp) {
;         const int base = 80 + grp * 144;
;         while (it < base + 80) { const int r = it - base; mla_item(cx, r / 5, r % 5, 7 - grp, lds, wv); it = next_item(ctr, slot, wv) - 32; }
;         SCHED_BARRIER();
;         while (it < base + 144) { const int r = it - base - 80; const int e = r & 31; nsa_item(cx, cflag, e >> 1, e & 1, (r < 32 ? 15 : 14) - 2 * grp, lds, wv); it = next_item(ctr, slot, wv) - 32; }
;       }
.LBB0_1349:
	s_add_i32 s0, s0, 1
	s_addk_i32 s87, 0xff00
	s_cmp_eq_u32 s0, 16
	s_cbranch_scc1 .LBB0_1496
.LBB0_1350:
	s_cmp_ge_u32 s0, 8
	s_cbranch_scc1 .Lq_mla_check
	s_lshl_b32 s2, s0, 6
	s_mov_b32 s86, s2
	s_branch .Lq_nsa_check
.Lq_mla_check:
	s_mul_i32 s2, s0, 0x50
	s_add_i32 s86, s2, 0xffffffd0
	s_add_i32 s3, s86, 0x50
	s_cmp_ge_i32 s8, s3
	s_cbranch_scc1 .LBB0_1349
	s_mov_b32 s24, s0
	s_sub_i32 s0, 15, s0
	s_lshl_b32 s87, s0, 8
	s_addk_i32 s87, 0x100
	s_lshl_b32 s15, s0, 2
	s_lshl_b32 s14, s0, 8
	s_add_i32 s15, s15, 4
	s_branch .LBB0_1354
